# dependency-wait poll back-off trim: the 20 s_sleep 2 in the intra-phase row-statistics flag waits replaced by s_nop 0
# baseline (speedup 1.0000x reference)
;     __device__ __forceinline__ void stats(const f32x4 (&v)[2][2][4][2], const Unit& u, int wr, int wc, int fr, int fq, LAS unsigned char* lds, int wid, int lane, const RmsX& e) const {
;     ...
;         if (wid == 0) { unsigned sp = 0;
;             while ((unsigned)__builtin_amdgcn_readfirstlane(__hip_atomic_load(e.cnt + 64 * u.pm, __ATOMIC_RELAXED, __HIP_MEMORY_SCOPE_AGENT)) < e.target) { __builtin_amdgcn_s_sleep(2); if (++sp > (1u << 22)) break; }
;             __builtin_amdgcn_fence(__ATOMIC_ACQUIRE, "agent"); }
.LBB0_247:
	global_load_dword v0, v2, s[30:31] sc1
	s_mov_b64 s[34:35], -1
	s_waitcnt vmcnt(0)
	v_readfirstlane_b32 s2, v0
	s_cmp_ge_u32 s2, s40
	s_cbranch_scc1 .LBB0_246
	s_nop 0
	global_load_dword v0, v2, s[30:31] sc1
	s_waitcnt vmcnt(0)
	v_readfirstlane_b32 s2, v0
	s_cmp_lt_u32 s2, s40
	s_cbranch_scc0 .LBB0_246
	s_nop 0
	global_load_dword v0, v2, s[30:31] sc1
	s_waitcnt vmcnt(0)
	v_readfirstlane_b32 s2, v0
	s_cmp_lt_u32 s2, s40
	s_cbranch_scc0 .LBB0_246
	s_nop 0
	global_load_dword v0, v2, s[30:31] sc1
	s_waitcnt vmcnt(0)
	v_readfirstlane_b32 s2, v0
	s_cmp_lt_u32 s2, s40
	s_cbranch_scc0 .LBB0_246
	s_nop 0
	global_load_dword v0, v2, s[30:31] sc1
	s_waitcnt vmcnt(0)
	v_readfirstlane_b32 s2, v0
	s_cmp_lt_u32 s2, s40
	s_cbranch_scc0 .LBB0_246
	s_add_i32 s0, s0, -5
	s_cmp_eq_u32 s0, 0
	s_cselect_b64 s[34:35], -1, 0
	s_nop 0
	s_branch .LBB0_246

;     __device__ __forceinline__ void stats(const f32x4 (&v)[2][2][4][2], const Unit& u, int wr, int wc, int fr, int fq, LAS unsigned char* lds, int wid, int lane, const RmsX& e) const {
;     ...
;         if (wid == 0) { unsigned sp = 0;
;             while ((unsigned)__builtin_amdgcn_readfirstlane(__hip_atomic_load(e.cnt + 64 * u.pm, __ATOMIC_RELAXED, __HIP_MEMORY_SCOPE_AGENT)) < e.target) { __builtin_amdgcn_s_sleep(2); if (++sp > (1u << 22)) break; }
;             __builtin_amdgcn_fence(__ATOMIC_ACQUIRE, "agent"); }
.LBB0_281:
	global_load_dword v132, v2, s[8:9] sc1
	s_mov_b64 s[14:15], -1
	s_waitcnt vmcnt(0)
	v_readfirstlane_b32 s2, v132
	s_cmp_ge_u32 s2, s40
	s_cbranch_scc1 .LBB0_280
	s_nop 0
	global_load_dword v132, v2, s[8:9] sc1
	s_waitcnt vmcnt(0)
	v_readfirstlane_b32 s2, v132
	s_cmp_lt_u32 s2, s40
	s_cbranch_scc0 .LBB0_280
	s_nop 0
	global_load_dword v132, v2, s[8:9] sc1
	s_waitcnt vmcnt(0)
	v_readfirstlane_b32 s2, v132
	s_cmp_lt_u32 s2, s40
	s_cbranch_scc0 .LBB0_280
	s_nop 0
	global_load_dword v132, v2, s[8:9] sc1
	s_waitcnt vmcnt(0)
	v_readfirstlane_b32 s2, v132
	s_cmp_lt_u32 s2, s40
	s_cbranch_scc0 .LBB0_280
	s_nop 0
	global_load_dword v132, v2, s[8:9] sc1
	s_waitcnt vmcnt(0)
	v_readfirstlane_b32 s2, v132
	s_cmp_lt_u32 s2, s40
	s_cbranch_scc0 .LBB0_280
	s_add_i32 s0, s0, -5
	s_cmp_eq_u32 s0, 0
	s_cselect_b64 s[14:15], -1, 0
	s_nop 0
	s_branch .LBB0_280

;     __device__ __forceinline__ void stats(const f32x4 (&v)[2][2][4][2], const Unit& u, int wr, int wc, int fr, int fq, LAS unsigned char* lds, int wid, int lane, const RmsX& e) const {
;     ...
;         if (wid == 0) { unsigned sp = 0;
;             while ((unsigned)__builtin_amdgcn_readfirstlane(__hip_atomic_load(e.cnt + 64 * u.pm, __ATOMIC_RELAXED, __HIP_MEMORY_SCOPE_AGENT)) < e.target) { __builtin_amdgcn_s_sleep(2); if (++sp > (1u << 22)) break; }
;             __builtin_amdgcn_fence(__ATOMIC_ACQUIRE, "agent"); }
.LBB0_481:
	global_load_dword v0, v2, s[10:11] sc1
	s_mov_b64 s[20:21], -1
	s_waitcnt vmcnt(0)
	v_readfirstlane_b32 s16, v0
	s_cmp_ge_u32 s16, s42
	s_cbranch_scc1 .LBB0_480
	s_nop 0
	global_load_dword v0, v2, s[10:11] sc1
	s_waitcnt vmcnt(0)
	v_readfirstlane_b32 s16, v0
	s_cmp_lt_u32 s16, s42
	s_cbranch_scc0 .LBB0_480
	s_nop 0
	global_load_dword v0, v2, s[10:11] sc1
	s_waitcnt vmcnt(0)
	v_readfirstlane_b32 s16, v0
	s_cmp_lt_u32 s16, s42
	s_cbranch_scc0 .LBB0_480
	s_nop 0
	global_load_dword v0, v2, s[10:11] sc1
	s_waitcnt vmcnt(0)
	v_readfirstlane_b32 s16, v0
	s_cmp_lt_u32 s16, s42
	s_cbranch_scc0 .LBB0_480
	s_nop 0
	global_load_dword v0, v2, s[10:11] sc1
	s_waitcnt vmcnt(0)
	v_readfirstlane_b32 s16, v0
	s_cmp_lt_u32 s16, s42
	s_cbranch_scc0 .LBB0_480
	s_add_i32 s15, s15, -5
	s_cmp_eq_u32 s15, 0
	s_cselect_b64 s[20:21], -1, 0
	s_nop 0
	s_branch .LBB0_480

;     __device__ __forceinline__ void stats(const f32x4 (&v)[2][2][4][2], const Unit& u, int wr, int wc, int fr, int fq, LAS unsigned char* lds, int wid, int lane, const RmsX& e) const {
;     ...
;         if (wid == 0) { unsigned sp = 0;
;             while ((unsigned)__builtin_amdgcn_readfirstlane(__hip_atomic_load(e.cnt + 64 * u.pm, __ATOMIC_RELAXED, __HIP_MEMORY_SCOPE_AGENT)) < e.target) { __builtin_amdgcn_s_sleep(2); if (++sp > (1u << 22)) break; }
;             __builtin_amdgcn_fence(__ATOMIC_ACQUIRE, "agent"); }
.LBB0_581:
	global_load_dword v132, v2, s[8:9] sc1
	s_waitcnt vmcnt(0)
	v_readfirstlane_b32 s12, v132
	s_cmp_ge_u32 s12, s42
	s_mov_b64 s[12:13], -1
	s_cbranch_scc1 .LBB0_580
	s_nop 0
	global_load_dword v132, v2, s[8:9] sc1
	s_waitcnt vmcnt(0)
	v_readfirstlane_b32 s12, v132
	s_cmp_lt_u32 s12, s42
	s_mov_b64 s[12:13], -1
	s_cbranch_scc0 .LBB0_580
	s_nop 0
	global_load_dword v132, v2, s[8:9] sc1
	s_waitcnt vmcnt(0)
	v_readfirstlane_b32 s12, v132
	s_cmp_lt_u32 s12, s42
	s_mov_b64 s[12:13], -1
	s_cbranch_scc0 .LBB0_580
	s_nop 0
	global_load_dword v132, v2, s[8:9] sc1
	s_waitcnt vmcnt(0)
	v_readfirstlane_b32 s12, v132
	s_cmp_lt_u32 s12, s42
	s_mov_b64 s[12:13], -1
	s_cbranch_scc0 .LBB0_580
	s_nop 0
	global_load_dword v132, v2, s[8:9] sc1
	s_waitcnt vmcnt(0)
	v_readfirstlane_b32 s12, v132
	s_cmp_lt_u32 s12, s42
	s_mov_b64 s[12:13], -1
	s_cbranch_scc0 .LBB0_580
	s_add_i32 s14, s14, -5
	s_cmp_eq_u32 s14, 0
	s_cselect_b64 s[12:13], -1, 0
	s_nop 0
	s_branch .LBB0_580
